# attention: static s_setprio 1 for waves 4-7 during the attention phase
# baseline (speedup 1.0000x reference)
.LBB0_494:
	v_readfirstlane_b32 s98, v194
	s_nop 3
	s_lshr_b32 s98, s98, 6
	s_cmp_ge_u32 s98, 4
	s_cbranch_scc0 .Latt_prio_skip
	s_setprio 1

.LBB0_566:
	s_setprio 0
	v_readlane_b32 s72, v254, 37
	v_readlane_b32 s73, v254, 38
	s_mov_b64 s[2:3], s[72:73]
	s_getreg_b32 s4, hwreg(HW_REG_XCC_ID, 0, 4)
	s_waitcnt vmcnt(0)
	s_waitcnt lgkmcnt(0)
	s_barrier
	s_mov_b64 s[0:1], exec
	v_readlane_b32 s74, v254, 40
	v_readlane_b32 s78, v254, 43
	v_readlane_b32 s80, v254, 45
	v_readlane_b32 s75, v254, 41
	v_readlane_b32 s79, v254, 44
	v_readlane_b32 s81, v254, 46
	v_readlane_b32 s58, v254, 48
	v_readlane_b32 s62, v254, 52
	s_and_b64 s[6:7], s[0:1], s[74:75]
	v_readlane_b32 s70, v254, 36
	v_readlane_b32 s76, v254, 42
	v_readlane_b32 s57, v254, 47
	v_readlane_b32 s59, v254, 49
	v_readlane_b32 s60, v254, 50
	v_readlane_b32 s61, v254, 51
	v_readlane_b32 s63, v254, 53
	v_readlane_b32 s64, v254, 54
	v_readlane_b32 s65, v254, 55
	s_movk_i32 s66, 0x80
	s_mov_b32 s67, 0x800000
	v_readlane_b32 s68, v254, 57
	v_readlane_b32 s69, v254, 56
	s_mov_b32 s77, 0x1fffe0
	s_mov_b32 s79, 0xbfb8aa3b
	s_mov_b32 s81, 0x40000
	s_mov_b32 s82, 0x48000
	s_mov_b32 s83, 0x50000
	s_mov_b32 s85, 0x3f2aaaab
	s_mov_b64 exec, s[6:7]
	s_cbranch_execz .LBB0_618
	v_mov_b32_e32 v0, s68
	s_load_dwordx2 s[2:3], s[2:3], 0x88
	s_waitcnt vmcnt(0) expcnt(0) lgkmcnt(0)
	ds_read_b32 v2, v0
	v_mov_b32_e32 v0, s69
	ds_read_b32 v0, v0
	s_and_b32 s33, s4, 15
	s_waitcnt lgkmcnt(1)
	v_cmp_ne_u32_e32 vcc, 0, v2
	s_cbranch_vccnz .LBB0_582
	s_add_u32 s4, s2, 0x4200
	s_addc_u32 s5, s3, 0
	s_add_u32 s6, s2, 0x4400
	s_addc_u32 s7, s3, 0
	s_add_u32 s8, s2, 0x4500
	s_addc_u32 s9, s3, 0
	s_add_u32 s10, s2, 0x4600
	s_addc_u32 s11, s3, 0
	s_add_u32 s12, s2, 0x4700
	s_addc_u32 s13, s3, 0
	s_add_u32 s14, s2, 0x4800
	s_addc_u32 s15, s3, 0
	s_add_u32 s16, s2, 0x4900
	s_addc_u32 s17, s3, 0
	s_add_u32 s18, s2, 0x4a00
	s_addc_u32 s19, s3, 0
	s_add_u32 s20, s2, 0x4b00
	s_addc_u32 s21, s3, 0
	s_add_u32 s22, s2, 0x4c00
	s_addc_u32 s23, s3, 0
	s_add_u32 s24, s2, 0x4d00
	s_addc_u32 s25, s3, 0
	s_add_u32 s26, s2, 0x4e00
	s_addc_u32 s27, s3, 0
	s_add_u32 s28, s2, 0x4f00
	s_addc_u32 s29, s3, 0
	s_add_u32 s30, s2, 0x5000
	s_addc_u32 s31, s3, 0
	s_add_u32 s34, s2, 0x5100
	s_addc_u32 s35, s3, 0
	s_add_u32 s36, s2, 0x5200
	s_addc_u32 s37, s3, 0
	s_add_u32 s38, s2, 0x5300
	s_addc_u32 s39, s3, 0
	s_mov_b32 s46, 1
	s_branch .LBB0_570
